# SGU mixer: split next-item prefetch (statistics+V before the MFMA chain, W_s after) combined with paired B-fragment reads
# speedup vs baseline: 1.0030x; 1.0030x over previous
.Lsgu_pfa_done:
	ds_read_b128 v[2:5], v183 offset:512
	ds_read_b128 v[186:189], v183 offset:544
	s_waitcnt vmcnt(29) lgkmcnt(1)
	v_mfma_f32_32x32x16_bf16 v[18:33], v[82:85], v[2:5], 0
	ds_read_b128 v[2:5], v183 offset:9216
	s_andn2_b64 vcc, exec, s[56:57]
	s_waitcnt vmcnt(28) lgkmcnt(1)
	v_mfma_f32_32x32x16_bf16 v[18:33], v[86:89], v[186:189], v[18:33]
	ds_read_b128 v[186:189], v183 offset:9248
	s_waitcnt lgkmcnt(1)
	v_mfma_f32_32x32x16_bf16 v[2:17], v[82:85], v[2:5], 0
	s_waitcnt lgkmcnt(0)
	v_mfma_f32_32x32x16_bf16 v[2:17], v[86:89], v[186:189], v[2:17]
	s_cbranch_vccnz .LBB0_133
	ds_read_b128 v[186:189], v183 offset:576
	ds_read_b128 v[194:197], v183 offset:9280
	s_waitcnt vmcnt(27) lgkmcnt(1)
	v_mfma_f32_32x32x16_bf16 v[18:33], v[90:93], v[186:189], v[18:33]
	s_waitcnt lgkmcnt(0)
	v_mfma_f32_32x32x16_bf16 v[2:17], v[90:93], v[194:197], v[2:17]

.LBB0_138:
	ds_read_b128 v[186:189], v183 offset:736
	ds_read_b128 v[194:197], v183 offset:9440
	s_waitcnt vmcnt(22) lgkmcnt(1)
	v_mfma_f32_32x32x16_bf16 v[18:33], v[110:113], v[186:189], v[18:33]
	s_waitcnt lgkmcnt(0)
	v_mfma_f32_32x32x16_bf16 v[2:17], v[110:113], v[194:197], v[2:17]

.LBB0_143:
	ds_read_b128 v[186:189], v183 offset:608
	ds_read_b128 v[194:197], v183 offset:9312
	s_waitcnt vmcnt(26) lgkmcnt(1)
	v_mfma_f32_32x32x16_bf16 v[18:33], v[94:97], v[186:189], v[18:33]
	s_waitcnt lgkmcnt(0)
	v_mfma_f32_32x32x16_bf16 v[2:17], v[94:97], v[194:197], v[2:17]
	s_andn2_b64 vcc, exec, s[86:87]
	s_cbranch_vccnz .LBB0_135
.LBB0_144:
	ds_read_b128 v[186:189], v183 offset:640
	ds_read_b128 v[194:197], v183 offset:9344
	s_waitcnt vmcnt(25) lgkmcnt(1)
	v_mfma_f32_32x32x16_bf16 v[18:33], v[98:101], v[186:189], v[18:33]
	s_waitcnt lgkmcnt(0)
	v_mfma_f32_32x32x16_bf16 v[2:17], v[98:101], v[194:197], v[2:17]
	s_andn2_b64 vcc, exec, s[88:89]
	s_cbranch_vccnz .LBB0_136
.LBB0_145:
	ds_read_b128 v[186:189], v183 offset:672
	ds_read_b128 v[194:197], v183 offset:9376
	s_waitcnt vmcnt(24) lgkmcnt(1)
	v_mfma_f32_32x32x16_bf16 v[18:33], v[102:105], v[186:189], v[18:33]
	s_waitcnt lgkmcnt(0)
	v_mfma_f32_32x32x16_bf16 v[2:17], v[102:105], v[194:197], v[2:17]
	v_cndmask_b32_e64 v185, 0, 1, s[90:91]
	v_cmp_ne_u32_e64 s[42:43], 1, v185
	s_andn2_b64 vcc, exec, s[90:91]
	s_cbranch_vccnz .LBB0_137
.LBB0_146:
	ds_read_b128 v[186:189], v183 offset:704
	ds_read_b128 v[194:197], v183 offset:9408
	s_waitcnt vmcnt(23) lgkmcnt(1)
	v_mfma_f32_32x32x16_bf16 v[18:33], v[106:109], v[186:189], v[18:33]
	s_waitcnt lgkmcnt(0)
	v_mfma_f32_32x32x16_bf16 v[2:17], v[106:109], v[194:197], v[2:17]
	s_and_b64 vcc, exec, s[42:43]
	s_cbranch_vccz .LBB0_138
	s_branch .LBB0_139
